# SSD next-chunk load addresses advanced incrementally, persistent pairs moved to v238-v247 (v222-v231 were live across the phase on some paths)
# baseline (speedup 1.0000x reference)
.LBB0_1040:
	s_xor_b64 s[24:25], s[22:23], -1
	s_xor_b64 s[22:23], s[78:79], -1
	s_add_i32 s47, s47, 1
	s_cmp_eq_u32 s35, 0
	s_cselect_b64 s[78:79], -1, 0
	s_andn2_b64 vcc, exec, s[24:25]
	s_mov_b64 s[24:25], -1
	s_cbranch_vccnz .LBB0_1113
	s_and_b64 s[24:25], s[78:79], exec
	s_mov_b32 s24, 0x1e400
	s_cselect_b32 s24, 0x1a000, s24
	v_add_u32_e32 v94, s24, v149
	s_waitcnt vmcnt(2)
	ds_read_b128 v[66:69], v94
	ds_read_b128 v[98:101], v161
	ds_read_b128 v[70:73], v94 offset:4352
	ds_read_b128 v[74:77], v94 offset:8704
	ds_read_b128 v[82:85], v94 offset:64
	ds_read_b128 v[102:105], v161 offset:64
	s_waitcnt lgkmcnt(4)
	v_mfma_f32_16x16x32_bf16 v[66:69], v[66:69], v[98:101], 0
	ds_read_b128 v[78:81], v94 offset:13056
	s_andn2_b64 vcc, exec, s[62:63]
	s_waitcnt lgkmcnt(4)
	v_mfma_f32_16x16x32_bf16 v[70:73], v[70:73], v[98:101], 0
	s_waitcnt lgkmcnt(1)
	v_mfma_f32_16x16x32_bf16 v[66:69], v[82:85], v[102:105], v[66:69]
	ds_read_b128 v[82:85], v94 offset:4416
	v_mfma_f32_16x16x32_bf16 v[74:77], v[74:77], v[98:101], 0
	s_waitcnt lgkmcnt(0)
	v_mfma_f32_16x16x32_bf16 v[70:73], v[82:85], v[102:105], v[70:73]
	ds_read_b128 v[82:85], v94 offset:8768
	v_mfma_f32_16x16x32_bf16 v[78:81], v[78:81], v[98:101], 0
	s_waitcnt lgkmcnt(0)
	v_mfma_f32_16x16x32_bf16 v[74:77], v[82:85], v[102:105], v[74:77]
	ds_read_b128 v[82:85], v94 offset:13120
	ds_read_b128 v[86:89], v94 offset:128
	s_waitcnt lgkmcnt(1)
	v_mfma_f32_16x16x32_bf16 v[78:81], v[82:85], v[102:105], v[78:81]
	ds_read_b128 v[106:109], v161 offset:128
	ds_read_b128 v[82:85], v94 offset:4480
	s_waitcnt lgkmcnt(1)
	v_mfma_f32_16x16x32_bf16 v[66:69], v[86:89], v[106:109], v[66:69]
	ds_read_b128 v[86:89], v94 offset:8832
	s_waitcnt lgkmcnt(1)
	v_mfma_f32_16x16x32_bf16 v[70:73], v[82:85], v[106:109], v[70:73]
	ds_read_b128 v[82:85], v94 offset:13184
	s_waitcnt lgkmcnt(1)
	v_mfma_f32_16x16x32_bf16 v[74:77], v[86:89], v[106:109], v[74:77]
	ds_read_b128 v[86:89], v94 offset:192
	ds_read_b128 v[90:93], v94 offset:4544
	ds_read_b128 v[110:113], v161 offset:192
	s_waitcnt lgkmcnt(3)
	v_mfma_f32_16x16x32_bf16 v[82:85], v[82:85], v[106:109], v[78:81]
	s_waitcnt lgkmcnt(0)
	v_mfma_f32_16x16x32_bf16 v[66:69], v[86:89], v[110:113], v[66:69]
	s_nop 0
	ds_read_b128 v[78:81], v94 offset:8896
	ds_read_b128 v[86:89], v94 offset:13248
	v_mfma_f32_16x16x32_bf16 v[70:73], v[90:93], v[110:113], v[70:73]
	s_waitcnt lgkmcnt(1)
	v_mfma_f32_16x16x32_bf16 v[78:81], v[78:81], v[110:113], v[74:77]
	s_waitcnt lgkmcnt(0)
	v_mfma_f32_16x16x32_bf16 v[74:77], v[86:89], v[110:113], v[82:85]
	s_cbranch_vccnz .LBB0_1043
	s_cmp_gt_u32 s47, 2
	s_cbranch_scc1 .Lmy_sdfast_a
	s_and_b64 s[24:25], s[92:93], exec
	s_cselect_b32 s24, 1, 35
	s_sub_i32 s24, s24, s47
	s_lshl_b32 s25, s24, 7
	s_or_b32 s26, s25, s0
	s_add_i32 s25, s25, s1
	s_cmp_lt_u32 s24, 2
	s_cselect_b32 s24, s26, s25
	v_add_u32_e32 v0, s24, v137
	v_ashrrev_i32_e32 v1, 31, v0
	v_lshlrev_b64 v[0:1], 13, v[0:1]
	v_add_u32_e32 v8, s24, v138
	v_lshl_add_u64 v[0:1], s[44:45], 0, v[0:1]
	s_mov_b32 s83, s67
	v_ashrrev_i32_e32 v9, 31, v8
	v_lshl_add_u64 v[0:1], v[0:1], 0, s[82:83]
	v_lshlrev_b64 v[8:9], 13, v[8:9]
	v_add_u32_e32 v16, s24, v139
	v_lshl_add_u64 v[0:1], v[0:1], 0, v[64:65]
	s_movk_i32 s25, 0x1000
	v_lshl_add_u64 v[8:9], s[44:45], 0, v[8:9]
	v_ashrrev_i32_e32 v17, 31, v16
	v_add_co_u32_e32 v4, vcc, s25, v0
	v_lshl_add_u64 v[8:9], v[8:9], 0, s[82:83]
	v_lshlrev_b64 v[16:17], 13, v[16:17]
	v_add_u32_e32 v24, s24, v140
	v_addc_co_u32_e32 v5, vcc, 0, v1, vcc
	v_lshl_add_u64 v[8:9], v[8:9], 0, v[64:65]
	v_lshl_add_u64 v[16:17], s[44:45], 0, v[16:17]
	v_ashrrev_i32_e32 v25, 31, v24
	v_add_co_u32_e32 v12, vcc, s25, v8
	v_lshl_add_u64 v[16:17], v[16:17], 0, s[82:83]
	v_lshlrev_b64 v[24:25], 13, v[24:25]
	v_addc_co_u32_e32 v13, vcc, 0, v9, vcc
	v_lshl_add_u64 v[16:17], v[16:17], 0, v[64:65]
	v_lshl_add_u64 v[24:25], s[44:45], 0, v[24:25]
	v_add_co_u32_e32 v20, vcc, s25, v16
	v_lshl_add_u64 v[24:25], v[24:25], 0, s[82:83]
	v_add_u32_e32 v32, s24, v136
	v_addc_co_u32_e32 v21, vcc, 0, v17, vcc
	v_lshl_add_u64 v[24:25], v[24:25], 0, v[64:65]
	v_ashrrev_i32_e32 v33, 31, v32
	v_add_co_u32_e32 v28, vcc, s25, v24
	v_lshlrev_b64 v[32:33], 13, v[32:33]
	s_nop 0
	v_addc_co_u32_e32 v29, vcc, 0, v25, vcc
	v_lshl_add_u64 v[36:37], v[130:131], 0, v[32:33]
	v_mov_b64_e32 v[238:239], v[4:5]
	v_mov_b64_e32 v[240:241], v[12:13]
	v_mov_b64_e32 v[242:243], v[20:21]
	v_mov_b64_e32 v[244:245], v[28:29]
	v_mov_b64_e32 v[246:247], v[36:37]
	s_branch .Lmy_sdload_a
.Lmy_sdfast_a:
	s_mov_b32 s83, s67
	s_mov_b32 s100, 0xfff00000
	s_mov_b32 s101, -1
	v_lshl_add_u64 v[238:239], v[238:239], 0, s[100:101]
	v_lshl_add_u64 v[240:241], v[240:241], 0, s[100:101]
	v_lshl_add_u64 v[242:243], v[242:243], 0, s[100:101]
	v_lshl_add_u64 v[244:245], v[244:245], 0, s[100:101]
	v_lshl_add_u64 v[246:247], v[246:247], 0, s[100:101]
.Lmy_sdload_a:
	global_load_dwordx4 v[0:3], v[238:239], off offset:2048
	global_load_dwordx4 v[4:7], v[238:239], off
	global_load_dwordx4 v[8:11], v[240:241], off offset:2048
	global_load_dwordx4 v[12:15], v[240:241], off
	global_load_dwordx4 v[16:19], v[242:243], off offset:2048
	global_load_dwordx4 v[20:23], v[242:243], off
	global_load_dwordx4 v[24:27], v[244:245], off offset:2048
	global_load_dwordx4 v[28:31], v[244:245], off
	global_load_dwordx4 v[32:35], v[246:247], off offset:16
	global_load_dwordx4 v[36:39], v[246:247], off
	s_mov_b32 s83, 0x41a00000

.LBB0_1113:
	s_and_b64 vcc, exec, s[24:25]
	s_cbranch_vccz .LBB0_1009
	s_and_b64 s[22:23], s[92:93], exec
	s_cselect_b32 s22, 1, 35
	s_sub_i32 s22, s22, s47
	s_lshl_b32 s23, s22, 7
	s_or_b32 s24, s23, s0
	s_add_i32 s23, s23, s1
	s_cmp_lt_u32 s22, 2
	s_cselect_b32 s22, s24, s23
	v_add_u32_e32 v0, s22, v137
	v_ashrrev_i32_e32 v1, 31, v0
	v_lshlrev_b64 v[0:1], 13, v[0:1]
	v_add_u32_e32 v8, s22, v138
	v_lshl_add_u64 v[0:1], s[44:45], 0, v[0:1]
	s_mov_b32 s83, s67
	v_ashrrev_i32_e32 v9, 31, v8
	v_lshl_add_u64 v[0:1], v[0:1], 0, s[82:83]
	v_lshlrev_b64 v[8:9], 13, v[8:9]
	v_add_u32_e32 v16, s22, v139
	v_lshl_add_u64 v[0:1], v[0:1], 0, v[64:65]
	s_movk_i32 s23, 0x1000
	v_lshl_add_u64 v[8:9], s[44:45], 0, v[8:9]
	v_ashrrev_i32_e32 v17, 31, v16
	v_add_co_u32_e32 v4, vcc, s23, v0
	v_lshl_add_u64 v[8:9], v[8:9], 0, s[82:83]
	v_lshlrev_b64 v[16:17], 13, v[16:17]
	v_add_u32_e32 v24, s22, v140
	v_addc_co_u32_e32 v5, vcc, 0, v1, vcc
	v_lshl_add_u64 v[8:9], v[8:9], 0, v[64:65]
	v_lshl_add_u64 v[16:17], s[44:45], 0, v[16:17]
	v_ashrrev_i32_e32 v25, 31, v24
	v_add_co_u32_e32 v12, vcc, s23, v8
	v_lshl_add_u64 v[16:17], v[16:17], 0, s[82:83]
	v_lshlrev_b64 v[24:25], 13, v[24:25]
	v_addc_co_u32_e32 v13, vcc, 0, v9, vcc
	v_lshl_add_u64 v[16:17], v[16:17], 0, v[64:65]
	v_lshl_add_u64 v[24:25], s[44:45], 0, v[24:25]
	v_add_co_u32_e32 v20, vcc, s23, v16
	v_lshl_add_u64 v[24:25], v[24:25], 0, s[82:83]
	v_add_u32_e32 v32, s22, v136
	v_addc_co_u32_e32 v21, vcc, 0, v17, vcc
	v_lshl_add_u64 v[24:25], v[24:25], 0, v[64:65]
	v_ashrrev_i32_e32 v33, 31, v32
	v_add_co_u32_e32 v28, vcc, s23, v24
	v_lshlrev_b64 v[32:33], 13, v[32:33]
	s_nop 0
	v_addc_co_u32_e32 v29, vcc, 0, v25, vcc
	v_lshl_add_u64 v[36:37], v[130:131], 0, v[32:33]
	v_mov_b64_e32 v[238:239], v[4:5]
	v_mov_b64_e32 v[240:241], v[12:13]
	v_mov_b64_e32 v[242:243], v[20:21]
	v_mov_b64_e32 v[244:245], v[28:29]
	v_mov_b64_e32 v[246:247], v[36:37]
	global_load_dwordx4 v[0:3], v[4:5], off offset:2048
	s_nop 0
	global_load_dwordx4 v[4:7], v[4:5], off
	s_nop 0
	global_load_dwordx4 v[8:11], v[12:13], off offset:2048
	s_nop 0
	global_load_dwordx4 v[12:15], v[12:13], off
	s_nop 0
	global_load_dwordx4 v[16:19], v[20:21], off offset:2048
	s_nop 0
	global_load_dwordx4 v[20:23], v[20:21], off
	s_nop 0
	global_load_dwordx4 v[24:27], v[28:29], off offset:2048
	s_nop 0
	global_load_dwordx4 v[28:31], v[28:29], off
	s_nop 0
	global_load_dwordx4 v[32:35], v[36:37], off offset:16
	s_nop 0
	global_load_dwordx4 v[36:39], v[36:37], off
	s_mov_b32 s83, 0x41a00000
	s_mov_b32 s26, s66
	s_branch .LBB0_1009

.LBB0_1162:
	s_xor_b64 s[24:25], s[22:23], -1
	s_xor_b64 s[36:37], s[36:37], -1
	s_add_i32 s26, s34, 1
	s_cmp_eq_u32 s83, 0
	s_cselect_b64 s[22:23], -1, 0
	s_andn2_b64 vcc, exec, s[24:25]
	s_mov_b64 s[24:25], -1
	s_cbranch_vccnz .LBB0_1235
	s_and_b64 s[24:25], s[22:23], exec
	s_mov_b32 s24, 0x1e400
	s_cselect_b32 s24, 0x1a000, s24
	v_add_u32_e32 v94, s24, v151
	s_waitcnt vmcnt(2)
	ds_read_b128 v[66:69], v94
	ds_read_b128 v[102:105], v161
	ds_read_b128 v[70:73], v94 offset:4352
	ds_read_b128 v[74:77], v94 offset:8704
	ds_read_b128 v[82:85], v94 offset:64
	ds_read_b128 v[106:109], v161 offset:64
	s_waitcnt lgkmcnt(4)
	v_mfma_f32_16x16x32_bf16 v[66:69], v[66:69], v[102:105], 0
	ds_read_b128 v[78:81], v94 offset:13056
	s_andn2_b64 vcc, exec, s[20:21]
	s_waitcnt lgkmcnt(4)
	v_mfma_f32_16x16x32_bf16 v[70:73], v[70:73], v[102:105], 0
	s_waitcnt lgkmcnt(1)
	v_mfma_f32_16x16x32_bf16 v[66:69], v[82:85], v[106:109], v[66:69]
	ds_read_b128 v[82:85], v94 offset:4416
	v_mfma_f32_16x16x32_bf16 v[74:77], v[74:77], v[102:105], 0
	s_waitcnt lgkmcnt(0)
	v_mfma_f32_16x16x32_bf16 v[70:73], v[82:85], v[106:109], v[70:73]
	ds_read_b128 v[82:85], v94 offset:8768
	v_mfma_f32_16x16x32_bf16 v[78:81], v[78:81], v[102:105], 0
	s_waitcnt lgkmcnt(0)
	v_mfma_f32_16x16x32_bf16 v[74:77], v[82:85], v[106:109], v[74:77]
	ds_read_b128 v[82:85], v94 offset:13120
	ds_read_b128 v[86:89], v94 offset:128
	s_waitcnt lgkmcnt(1)
	v_mfma_f32_16x16x32_bf16 v[78:81], v[82:85], v[106:109], v[78:81]
	ds_read_b128 v[110:113], v161 offset:128
	ds_read_b128 v[82:85], v94 offset:4480
	s_waitcnt lgkmcnt(1)
	v_mfma_f32_16x16x32_bf16 v[66:69], v[86:89], v[110:113], v[66:69]
	ds_read_b128 v[86:89], v94 offset:8832
	s_waitcnt lgkmcnt(1)
	v_mfma_f32_16x16x32_bf16 v[70:73], v[82:85], v[110:113], v[70:73]
	ds_read_b128 v[82:85], v94 offset:13184
	s_waitcnt lgkmcnt(1)
	v_mfma_f32_16x16x32_bf16 v[86:89], v[86:89], v[110:113], v[74:77]
	s_nop 2
	ds_read_b128 v[74:77], v94 offset:192
	ds_read_b128 v[90:93], v94 offset:4544
	ds_read_b128 v[126:129], v161 offset:192
	s_waitcnt lgkmcnt(3)
	v_mfma_f32_16x16x32_bf16 v[82:85], v[82:85], v[110:113], v[78:81]
	s_waitcnt lgkmcnt(0)
	v_mfma_f32_16x16x32_bf16 v[78:81], v[74:77], v[126:129], v[66:69]
	s_nop 2
	ds_read_b128 v[66:69], v94 offset:8896
	v_mfma_f32_16x16x32_bf16 v[74:77], v[90:93], v[126:129], v[70:73]
	ds_read_b128 v[90:93], v94 offset:13248
	s_waitcnt lgkmcnt(1)
	v_mfma_f32_16x16x32_bf16 v[70:73], v[66:69], v[126:129], v[86:89]
	s_waitcnt lgkmcnt(0)
	v_mfma_f32_16x16x32_bf16 v[66:69], v[90:93], v[126:129], v[82:85]
	s_cbranch_vccnz .LBB0_1165
	s_cmp_gt_u32 s34, 1
	s_cbranch_scc1 .Lmy_sdfast_b
	s_lshl_b32 s24, s26, 7
	s_and_b64 s[20:21], s[56:57], exec
	s_movk_i32 s21, 0xff00
	s_cselect_b32 s20, 8, 12
	s_cselect_b32 s21, 0x4000, s21
	s_lshl_b32 s20, s31, s20
	s_add_i32 s21, s24, s21
	s_add_i32 s21, s21, s20
	v_add_u32_e32 v0, s21, v139
	v_ashrrev_i32_e32 v1, 31, v0
	v_lshlrev_b64 v[0:1], 13, v[0:1]
	v_add_u32_e32 v8, s21, v140
	v_lshl_add_u64 v[0:1], s[44:45], 0, v[0:1]
	s_mov_b32 s83, s67
	v_ashrrev_i32_e32 v9, 31, v8
	v_lshl_add_u64 v[0:1], v[0:1], 0, s[82:83]
	v_lshlrev_b64 v[8:9], 13, v[8:9]
	v_add_u32_e32 v16, s21, v141
	v_lshl_add_u64 v[0:1], v[0:1], 0, v[64:65]
	s_movk_i32 s20, 0x1000
	v_lshl_add_u64 v[8:9], s[44:45], 0, v[8:9]
	v_ashrrev_i32_e32 v17, 31, v16
	v_add_co_u32_e32 v4, vcc, s20, v0
	v_lshl_add_u64 v[8:9], v[8:9], 0, s[82:83]
	v_lshlrev_b64 v[16:17], 13, v[16:17]
	v_add_u32_e32 v24, s21, v142
	v_addc_co_u32_e32 v5, vcc, 0, v1, vcc
	v_lshl_add_u64 v[8:9], v[8:9], 0, v[64:65]
	v_lshl_add_u64 v[16:17], s[44:45], 0, v[16:17]
	v_ashrrev_i32_e32 v25, 31, v24
	v_add_co_u32_e32 v12, vcc, s20, v8
	v_lshl_add_u64 v[16:17], v[16:17], 0, s[82:83]
	v_lshlrev_b64 v[24:25], 13, v[24:25]
	v_addc_co_u32_e32 v13, vcc, 0, v9, vcc
	v_lshl_add_u64 v[16:17], v[16:17], 0, v[64:65]
	v_lshl_add_u64 v[24:25], s[44:45], 0, v[24:25]
	v_add_co_u32_e32 v20, vcc, s20, v16
	v_lshl_add_u64 v[24:25], v[24:25], 0, s[82:83]
	v_add_u32_e32 v32, s21, v138
	v_addc_co_u32_e32 v21, vcc, 0, v17, vcc
	v_lshl_add_u64 v[24:25], v[24:25], 0, v[64:65]
	v_ashrrev_i32_e32 v33, 31, v32
	v_add_co_u32_e32 v28, vcc, s20, v24
	v_lshlrev_b64 v[32:33], 13, v[32:33]
	s_nop 0
	v_addc_co_u32_e32 v29, vcc, 0, v25, vcc
	v_lshl_add_u64 v[36:37], v[132:133], 0, v[32:33]
	v_mov_b64_e32 v[238:239], v[4:5]
	v_mov_b64_e32 v[240:241], v[12:13]
	v_mov_b64_e32 v[242:243], v[20:21]
	v_mov_b64_e32 v[244:245], v[28:29]
	v_mov_b64_e32 v[246:247], v[36:37]
	s_branch .Lmy_sdload_b
.Lmy_sdfast_b:
	s_mov_b32 s83, s67
	s_mov_b32 s100, 0x100000
	s_mov_b32 s101, 0
	v_lshl_add_u64 v[238:239], v[238:239], 0, s[100:101]
	v_lshl_add_u64 v[240:241], v[240:241], 0, s[100:101]
	v_lshl_add_u64 v[242:243], v[242:243], 0, s[100:101]
	v_lshl_add_u64 v[244:245], v[244:245], 0, s[100:101]
	v_lshl_add_u64 v[246:247], v[246:247], 0, s[100:101]
.Lmy_sdload_b:
	global_load_dwordx4 v[0:3], v[238:239], off offset:2048
	global_load_dwordx4 v[4:7], v[238:239], off
	global_load_dwordx4 v[8:11], v[240:241], off offset:2048
	global_load_dwordx4 v[12:15], v[240:241], off
	global_load_dwordx4 v[16:19], v[242:243], off offset:2048
	global_load_dwordx4 v[20:23], v[242:243], off
	global_load_dwordx4 v[24:27], v[244:245], off offset:2048
	global_load_dwordx4 v[28:31], v[244:245], off
	global_load_dwordx4 v[32:35], v[246:247], off offset:16
	global_load_dwordx4 v[36:39], v[246:247], off

.LBB0_1235:
	s_and_b64 vcc, exec, s[24:25]
	s_cbranch_vccz .LBB0_1237
	s_lshl_b32 s24, s26, 7
	s_and_b64 s[20:21], s[56:57], exec
	s_movk_i32 s21, 0xff00
	s_cselect_b32 s20, 8, 12
	s_cselect_b32 s21, 0x4000, s21
	s_lshl_b32 s20, s31, s20
	s_add_i32 s21, s24, s21
	s_add_i32 s21, s21, s20
	v_add_u32_e32 v0, s21, v139
	v_ashrrev_i32_e32 v1, 31, v0
	v_lshlrev_b64 v[0:1], 13, v[0:1]
	v_add_u32_e32 v8, s21, v140
	v_lshl_add_u64 v[0:1], s[44:45], 0, v[0:1]
	s_mov_b32 s83, s67
	v_ashrrev_i32_e32 v9, 31, v8
	v_lshl_add_u64 v[0:1], v[0:1], 0, s[82:83]
	v_lshlrev_b64 v[8:9], 13, v[8:9]
	v_add_u32_e32 v16, s21, v141
	v_lshl_add_u64 v[0:1], v[0:1], 0, v[64:65]
	s_movk_i32 s20, 0x1000
	v_lshl_add_u64 v[8:9], s[44:45], 0, v[8:9]
	v_ashrrev_i32_e32 v17, 31, v16
	v_add_co_u32_e32 v4, vcc, s20, v0
	v_lshl_add_u64 v[8:9], v[8:9], 0, s[82:83]
	v_lshlrev_b64 v[16:17], 13, v[16:17]
	v_add_u32_e32 v24, s21, v142
	v_addc_co_u32_e32 v5, vcc, 0, v1, vcc
	v_lshl_add_u64 v[8:9], v[8:9], 0, v[64:65]
	v_lshl_add_u64 v[16:17], s[44:45], 0, v[16:17]
	v_ashrrev_i32_e32 v25, 31, v24
	v_add_co_u32_e32 v12, vcc, s20, v8
	v_lshl_add_u64 v[16:17], v[16:17], 0, s[82:83]
	v_lshlrev_b64 v[24:25], 13, v[24:25]
	v_addc_co_u32_e32 v13, vcc, 0, v9, vcc
	v_lshl_add_u64 v[16:17], v[16:17], 0, v[64:65]
	v_lshl_add_u64 v[24:25], s[44:45], 0, v[24:25]
	v_add_co_u32_e32 v20, vcc, s20, v16
	v_lshl_add_u64 v[24:25], v[24:25], 0, s[82:83]
	v_add_u32_e32 v32, s21, v138
	v_addc_co_u32_e32 v21, vcc, 0, v17, vcc
	v_lshl_add_u64 v[24:25], v[24:25], 0, v[64:65]
	v_ashrrev_i32_e32 v33, 31, v32
	v_add_co_u32_e32 v28, vcc, s20, v24
	v_lshlrev_b64 v[32:33], 13, v[32:33]
	s_nop 0
	v_addc_co_u32_e32 v29, vcc, 0, v25, vcc
	v_lshl_add_u64 v[36:37], v[132:133], 0, v[32:33]
	v_mov_b64_e32 v[238:239], v[4:5]
	v_mov_b64_e32 v[240:241], v[12:13]
	v_mov_b64_e32 v[242:243], v[20:21]
	v_mov_b64_e32 v[244:245], v[28:29]
	v_mov_b64_e32 v[246:247], v[36:37]
	global_load_dwordx4 v[0:3], v[4:5], off offset:2048
	s_nop 0
	global_load_dwordx4 v[4:7], v[4:5], off
	s_nop 0
	global_load_dwordx4 v[8:11], v[12:13], off offset:2048
	s_nop 0
	global_load_dwordx4 v[12:15], v[12:13], off
	s_nop 0
	global_load_dwordx4 v[16:19], v[20:21], off offset:2048
	s_nop 0
	global_load_dwordx4 v[20:23], v[20:21], off
	s_nop 0
	global_load_dwordx4 v[24:27], v[28:29], off offset:2048
	s_nop 0
	global_load_dwordx4 v[28:31], v[28:29], off
	s_nop 0
	global_load_dwordx4 v[32:35], v[36:37], off offset:16
	s_nop 0
	global_load_dwordx4 v[36:39], v[36:37], off
	s_mov_b32 s27, s76
